# gate-up epilogues (phases 1, 9) rewritten: packed f32 mul/fma, saddr stores with one offset mad, two-group software pipeline
# speedup vs baseline: 1.0079x; 1.0079x over previous
; DI float fast_exp2(float x) { return __builtin_amdgcn_exp2f(x); }
; DI float fast_rcp(float x) { return __builtin_amdgcn_rcpf(x); }
;     DI void operator()(Acc& acc, const pg8::Unit& u, int wr, int wc, int fr, int fq, const Pre& pr) const {
;         const int col = u.pn * 128 + wc * 32 + fq * 8;
; #pragma unroll
;         for (int ai = 0; ai < 2; ++ai)
; #pragma unroll
;             for (int m = 0; m < 4; ++m) {
;                 const int row = u.pm * 256 + ai * 128 + wr * 64 + m * 16 + fr;
;                 const float msq = msq_of(pr.v[ai * 4 + m]), nrl = -1.4426950408889634f * __builtin_amdgcn_rsqf(msq);
;                 f32x4 h[2];
; #pragma unroll
;                 for (int n = 0; n < 2; ++n)
; #pragma unroll
;                     for (int i = 0; i < 4; ++i) { const float ga = acc[ai][0][m][n][i], ua = acc[ai][1][m][n][i];
;                         const float e = fast_exp2(ga * nrl); h[n][i] = (ga * ua) * fast_rcp(__builtin_fmaf(e, msq, msq)); }
;                 store8(H + (size_t)row * FF + col, h[0], h[1]);
;             }
.LBB0_182:
	s_waitcnt vmcnt(0)
	v_fmamk_f32 v186, v166, 0x3a800000, v161
	v_rsq_f32_e32 v189, v186
	v_lshl_or_b32 v202, s60, 7, v159
	v_lshlrev_b32_e32 v202, 1, v202
	v_mad_u32_u24 v194, v156, s59, v202
	v_mul_f32_e32 v188, 0xbfb8aa3b, v189
	v_fmamk_f32 v190, v165, 0x3a800000, v161
	v_rsq_f32_e32 v193, v190
	v_add_u32_e32 v195, 0x16000, v194
	v_add_u32_e32 v196, 0x2c000, v194
	v_add_u32_e32 v197, 0x42000, v194
	v_add_u32_e32 v198, 0xb0000, v194
	v_add_u32_e32 v199, 0xc6000, v194
	v_add_u32_e32 v200, 0xdc000, v194
	v_add_u32_e32 v201, 0xf2000, v194
	v_mul_f32_e32 v192, 0xbfb8aa3b, v193
	v_pk_mul_f32 v[122:123], v[126:127], v[122:123]
	v_pk_mul_f32 v[124:125], v[128:129], v[124:125]
	v_pk_mul_f32 v[114:115], v[118:119], v[114:115]
	v_pk_mul_f32 v[116:117], v[120:121], v[116:117]
	v_pk_mul_f32 v[126:127], v[126:127], v[188:189] op_sel_hi:[1,0]
	v_pk_mul_f32 v[128:129], v[128:129], v[188:189] op_sel_hi:[1,0]
	v_pk_mul_f32 v[118:119], v[118:119], v[188:189] op_sel_hi:[1,0]
	v_pk_mul_f32 v[120:121], v[120:121], v[188:189] op_sel_hi:[1,0]
	v_exp_f32_e32 v126, v126
	v_exp_f32_e32 v127, v127
	v_exp_f32_e32 v128, v128
	v_exp_f32_e32 v129, v129
	v_exp_f32_e32 v118, v118
	v_exp_f32_e32 v119, v119
	v_exp_f32_e32 v120, v120
	v_exp_f32_e32 v121, v121
	v_pk_fma_f32 v[126:127], v[126:127], v[186:187], v[186:187] op_sel_hi:[1,0,0]
	v_pk_fma_f32 v[128:129], v[128:129], v[186:187], v[186:187] op_sel_hi:[1,0,0]
	v_pk_fma_f32 v[118:119], v[118:119], v[186:187], v[186:187] op_sel_hi:[1,0,0]
	v_pk_fma_f32 v[120:121], v[120:121], v[186:187], v[186:187] op_sel_hi:[1,0,0]
	v_rcp_f32_e32 v126, v126
	v_rcp_f32_e32 v127, v127
	v_rcp_f32_e32 v128, v128
	v_rcp_f32_e32 v129, v129
	v_rcp_f32_e32 v118, v118
	v_rcp_f32_e32 v119, v119
	v_rcp_f32_e32 v120, v120
	v_rcp_f32_e32 v121, v121
	v_fmamk_f32 v186, v164, 0x3a800000, v161
	v_rsq_f32_e32 v189, v186
	v_pk_mul_f32 v[122:123], v[126:127], v[122:123]
	v_pk_mul_f32 v[124:125], v[128:129], v[124:125]
	v_pk_mul_f32 v[114:115], v[118:119], v[114:115]
	v_pk_mul_f32 v[116:117], v[120:121], v[116:117]
	v_cvt_pk_bf16_f32 v126, v122, v123
	v_cvt_pk_bf16_f32 v127, v124, v125
	v_cvt_pk_bf16_f32 v128, v114, v115
	v_cvt_pk_bf16_f32 v129, v116, v117
	v_mul_f32_e32 v188, 0xbfb8aa3b, v189
	v_pk_mul_f32 v[106:107], v[110:111], v[106:107]
	v_pk_mul_f32 v[108:109], v[112:113], v[108:109]
	v_pk_mul_f32 v[98:99], v[102:103], v[98:99]
	v_pk_mul_f32 v[100:101], v[104:105], v[100:101]
	v_pk_mul_f32 v[110:111], v[110:111], v[192:193] op_sel_hi:[1,0]
	v_pk_mul_f32 v[112:113], v[112:113], v[192:193] op_sel_hi:[1,0]
	v_pk_mul_f32 v[102:103], v[102:103], v[192:193] op_sel_hi:[1,0]
	v_pk_mul_f32 v[104:105], v[104:105], v[192:193] op_sel_hi:[1,0]
	v_exp_f32_e32 v110, v110
	v_exp_f32_e32 v111, v111
	v_exp_f32_e32 v112, v112
	v_exp_f32_e32 v113, v113
	v_exp_f32_e32 v102, v102
	v_exp_f32_e32 v103, v103
	v_exp_f32_e32 v104, v104
	v_exp_f32_e32 v105, v105
	global_store_dwordx4 v194, v[126:129], s[10:11]
	v_pk_fma_f32 v[110:111], v[110:111], v[190:191], v[190:191] op_sel_hi:[1,0,0]
	v_pk_fma_f32 v[112:113], v[112:113], v[190:191], v[190:191] op_sel_hi:[1,0,0]
	v_pk_fma_f32 v[102:103], v[102:103], v[190:191], v[190:191] op_sel_hi:[1,0,0]
	v_pk_fma_f32 v[104:105], v[104:105], v[190:191], v[190:191] op_sel_hi:[1,0,0]
	v_rcp_f32_e32 v110, v110
	v_rcp_f32_e32 v111, v111
	v_rcp_f32_e32 v112, v112
	v_rcp_f32_e32 v113, v113
	v_rcp_f32_e32 v102, v102
	v_rcp_f32_e32 v103, v103
	v_rcp_f32_e32 v104, v104
	v_rcp_f32_e32 v105, v105
	v_fmamk_f32 v190, v157, 0x3a800000, v161
	v_rsq_f32_e32 v193, v190
	v_pk_mul_f32 v[106:107], v[110:111], v[106:107]
	v_pk_mul_f32 v[108:109], v[112:113], v[108:109]
	v_pk_mul_f32 v[98:99], v[102:103], v[98:99]
	v_pk_mul_f32 v[100:101], v[104:105], v[100:101]
	v_cvt_pk_bf16_f32 v110, v106, v107
	v_cvt_pk_bf16_f32 v111, v108, v109
	v_cvt_pk_bf16_f32 v112, v98, v99
	v_cvt_pk_bf16_f32 v113, v100, v101
	v_mul_f32_e32 v192, 0xbfb8aa3b, v193
	v_pk_mul_f32 v[90:91], v[94:95], v[90:91]
	v_pk_mul_f32 v[92:93], v[96:97], v[92:93]
	v_pk_mul_f32 v[82:83], v[86:87], v[82:83]
	v_pk_mul_f32 v[84:85], v[88:89], v[84:85]
	v_pk_mul_f32 v[94:95], v[94:95], v[188:189] op_sel_hi:[1,0]
	v_pk_mul_f32 v[96:97], v[96:97], v[188:189] op_sel_hi:[1,0]
	v_pk_mul_f32 v[86:87], v[86:87], v[188:189] op_sel_hi:[1,0]
	v_pk_mul_f32 v[88:89], v[88:89], v[188:189] op_sel_hi:[1,0]
	v_exp_f32_e32 v94, v94
	v_exp_f32_e32 v95, v95
	v_exp_f32_e32 v96, v96
	v_exp_f32_e32 v97, v97
	v_exp_f32_e32 v86, v86
	v_exp_f32_e32 v87, v87
	v_exp_f32_e32 v88, v88
	v_exp_f32_e32 v89, v89
	global_store_dwordx4 v195, v[110:113], s[10:11]
	v_pk_fma_f32 v[94:95], v[94:95], v[186:187], v[186:187] op_sel_hi:[1,0,0]
	v_pk_fma_f32 v[96:97], v[96:97], v[186:187], v[186:187] op_sel_hi:[1,0,0]
	v_pk_fma_f32 v[86:87], v[86:87], v[186:187], v[186:187] op_sel_hi:[1,0,0]
	v_pk_fma_f32 v[88:89], v[88:89], v[186:187], v[186:187] op_sel_hi:[1,0,0]
	v_rcp_f32_e32 v94, v94
	v_rcp_f32_e32 v95, v95
	v_rcp_f32_e32 v96, v96
	v_rcp_f32_e32 v97, v97
	v_rcp_f32_e32 v86, v86
	v_rcp_f32_e32 v87, v87
	v_rcp_f32_e32 v88, v88
	v_rcp_f32_e32 v89, v89
	v_fmamk_f32 v186, v155, 0x3a800000, v161
	v_rsq_f32_e32 v189, v186
	v_pk_mul_f32 v[90:91], v[94:95], v[90:91]
	v_pk_mul_f32 v[92:93], v[96:97], v[92:93]
	v_pk_mul_f32 v[82:83], v[86:87], v[82:83]
	v_pk_mul_f32 v[84:85], v[88:89], v[84:85]
	v_cvt_pk_bf16_f32 v94, v90, v91
	v_cvt_pk_bf16_f32 v95, v92, v93
	v_cvt_pk_bf16_f32 v96, v82, v83
	v_cvt_pk_bf16_f32 v97, v84, v85
	v_mul_f32_e32 v188, 0xbfb8aa3b, v189
	v_pk_mul_f32 v[74:75], v[78:79], v[74:75]
	v_pk_mul_f32 v[76:77], v[80:81], v[76:77]
	v_pk_mul_f32 v[66:67], v[70:71], v[66:67]
	v_pk_mul_f32 v[68:69], v[72:73], v[68:69]
; DI float fast_exp2(float x) { return __builtin_amdgcn_exp2f(x); }
; DI float fast_rcp(float x) { return __builtin_amdgcn_rcpf(x); }
;     DI void operator()(Acc& acc, const pg8::Unit& u, int wr, int wc, int fr, int fq, const Pre& pr) const {
;         const int col = u.pn * 128 + wc * 32 + fq * 8;
; #pragma unroll
;         for (int ai = 0; ai < 2; ++ai)
; #pragma unroll
;             for (int m = 0; m < 4; ++m) {
;                 const int row = u.pm * 256 + ai * 128 + wr * 64 + m * 16 + fr;
;                 const float msq = msq_of(pr.v[ai * 4 + m]), nrl = -1.4426950408889634f * __builtin_amdgcn_rsqf(msq);
;                 f32x4 h[2];
; #pragma unroll
;                 for (int n = 0; n < 2; ++n)
; #pragma unroll
;                     for (int i = 0; i < 4; ++i) { const float ga = acc[ai][0][m][n][i], ua = acc[ai][1][m][n][i];
;                         const float e = fast_exp2(ga * nrl); h[n][i] = (ga * ua) * fast_rcp(__builtin_fmaf(e, msq, msq)); }
;                 store8(H + (size_t)row * FF + col, h[0], h[1]);
;             }
	v_pk_mul_f32 v[78:79], v[78:79], v[192:193] op_sel_hi:[1,0]
	v_pk_mul_f32 v[80:81], v[80:81], v[192:193] op_sel_hi:[1,0]
	v_pk_mul_f32 v[70:71], v[70:71], v[192:193] op_sel_hi:[1,0]
	v_pk_mul_f32 v[72:73], v[72:73], v[192:193] op_sel_hi:[1,0]
	v_exp_f32_e32 v78, v78
	v_exp_f32_e32 v79, v79
	v_exp_f32_e32 v80, v80
	v_exp_f32_e32 v81, v81
	v_exp_f32_e32 v70, v70
	v_exp_f32_e32 v71, v71
	v_exp_f32_e32 v72, v72
	v_exp_f32_e32 v73, v73
	global_store_dwordx4 v196, v[94:97], s[10:11]
	v_pk_fma_f32 v[78:79], v[78:79], v[190:191], v[190:191] op_sel_hi:[1,0,0]
	v_pk_fma_f32 v[80:81], v[80:81], v[190:191], v[190:191] op_sel_hi:[1,0,0]
	v_pk_fma_f32 v[70:71], v[70:71], v[190:191], v[190:191] op_sel_hi:[1,0,0]
	v_pk_fma_f32 v[72:73], v[72:73], v[190:191], v[190:191] op_sel_hi:[1,0,0]
	v_rcp_f32_e32 v78, v78
	v_rcp_f32_e32 v79, v79
	v_rcp_f32_e32 v80, v80
	v_rcp_f32_e32 v81, v81
	v_rcp_f32_e32 v70, v70
	v_rcp_f32_e32 v71, v71
	v_rcp_f32_e32 v72, v72
	v_rcp_f32_e32 v73, v73
	v_fmamk_f32 v190, v153, 0x3a800000, v161
	v_rsq_f32_e32 v193, v190
	v_pk_mul_f32 v[74:75], v[78:79], v[74:75]
	v_pk_mul_f32 v[76:77], v[80:81], v[76:77]
	v_pk_mul_f32 v[66:67], v[70:71], v[66:67]
	v_pk_mul_f32 v[68:69], v[72:73], v[68:69]
	v_cvt_pk_bf16_f32 v78, v74, v75
	v_cvt_pk_bf16_f32 v79, v76, v77
	v_cvt_pk_bf16_f32 v80, v66, v67
	v_cvt_pk_bf16_f32 v81, v68, v69
	v_mul_f32_e32 v192, 0xbfb8aa3b, v193
	v_pk_mul_f32 v[58:59], v[62:63], v[58:59]
	v_pk_mul_f32 v[60:61], v[64:65], v[60:61]
	v_pk_mul_f32 v[50:51], v[54:55], v[50:51]
	v_pk_mul_f32 v[52:53], v[56:57], v[52:53]
	v_pk_mul_f32 v[62:63], v[62:63], v[188:189] op_sel_hi:[1,0]
	v_pk_mul_f32 v[64:65], v[64:65], v[188:189] op_sel_hi:[1,0]
	v_pk_mul_f32 v[54:55], v[54:55], v[188:189] op_sel_hi:[1,0]
	v_pk_mul_f32 v[56:57], v[56:57], v[188:189] op_sel_hi:[1,0]
	v_exp_f32_e32 v62, v62
	v_exp_f32_e32 v63, v63
	v_exp_f32_e32 v64, v64
	v_exp_f32_e32 v65, v65
	v_exp_f32_e32 v54, v54
	v_exp_f32_e32 v55, v55
	v_exp_f32_e32 v56, v56
	v_exp_f32_e32 v57, v57
	global_store_dwordx4 v197, v[78:81], s[10:11]
	v_pk_fma_f32 v[62:63], v[62:63], v[186:187], v[186:187] op_sel_hi:[1,0,0]
	v_pk_fma_f32 v[64:65], v[64:65], v[186:187], v[186:187] op_sel_hi:[1,0,0]
	v_pk_fma_f32 v[54:55], v[54:55], v[186:187], v[186:187] op_sel_hi:[1,0,0]
	v_pk_fma_f32 v[56:57], v[56:57], v[186:187], v[186:187] op_sel_hi:[1,0,0]
	v_rcp_f32_e32 v62, v62
	v_rcp_f32_e32 v63, v63
	v_rcp_f32_e32 v64, v64
	v_rcp_f32_e32 v65, v65
	v_rcp_f32_e32 v54, v54
	v_rcp_f32_e32 v55, v55
	v_rcp_f32_e32 v56, v56
	v_rcp_f32_e32 v57, v57
	v_fmamk_f32 v186, v151, 0x3a800000, v161
	v_rsq_f32_e32 v189, v186
	v_pk_mul_f32 v[58:59], v[62:63], v[58:59]
	v_pk_mul_f32 v[60:61], v[64:65], v[60:61]
	v_pk_mul_f32 v[50:51], v[54:55], v[50:51]
	v_pk_mul_f32 v[52:53], v[56:57], v[52:53]
	v_cvt_pk_bf16_f32 v62, v58, v59
	v_cvt_pk_bf16_f32 v63, v60, v61
	v_cvt_pk_bf16_f32 v64, v50, v51
	v_cvt_pk_bf16_f32 v65, v52, v53
	v_mul_f32_e32 v188, 0xbfb8aa3b, v189
	v_pk_mul_f32 v[42:43], v[46:47], v[42:43]
	v_pk_mul_f32 v[44:45], v[48:49], v[44:45]
	v_pk_mul_f32 v[34:35], v[38:39], v[34:35]
	v_pk_mul_f32 v[36:37], v[40:41], v[36:37]
	v_pk_mul_f32 v[46:47], v[46:47], v[192:193] op_sel_hi:[1,0]
	v_pk_mul_f32 v[48:49], v[48:49], v[192:193] op_sel_hi:[1,0]
	v_pk_mul_f32 v[38:39], v[38:39], v[192:193] op_sel_hi:[1,0]
	v_pk_mul_f32 v[40:41], v[40:41], v[192:193] op_sel_hi:[1,0]
	v_exp_f32_e32 v46, v46
	v_exp_f32_e32 v47, v47
	v_exp_f32_e32 v48, v48
	v_exp_f32_e32 v49, v49
	v_exp_f32_e32 v38, v38
	v_exp_f32_e32 v39, v39
	v_exp_f32_e32 v40, v40
	v_exp_f32_e32 v41, v41
	global_store_dwordx4 v198, v[62:65], s[10:11]
	v_pk_fma_f32 v[46:47], v[46:47], v[190:191], v[190:191] op_sel_hi:[1,0,0]
	v_pk_fma_f32 v[48:49], v[48:49], v[190:191], v[190:191] op_sel_hi:[1,0,0]
; DI float fast_exp2(float x) { return __builtin_amdgcn_exp2f(x); }
; DI float fast_rcp(float x) { return __builtin_amdgcn_rcpf(x); }
;     DI void operator()(Acc& acc, const pg8::Unit& u, int wr, int wc, int fr, int fq, const Pre& pr) const {
;         const int col = u.pn * 128 + wc * 32 + fq * 8;
; #pragma unroll
;         for (int ai = 0; ai < 2; ++ai)
; #pragma unroll
;             for (int m = 0; m < 4; ++m) {
;                 const int row = u.pm * 256 + ai * 128 + wr * 64 + m * 16 + fr;
;                 const float msq = msq_of(pr.v[ai * 4 + m]), nrl = -1.4426950408889634f * __builtin_amdgcn_rsqf(msq);
;                 f32x4 h[2];
; #pragma unroll
;                 for (int n = 0; n < 2; ++n)
; #pragma unroll
;                     for (int i = 0; i < 4; ++i) { const float ga = acc[ai][0][m][n][i], ua = acc[ai][1][m][n][i];
;                         const float e = fast_exp2(ga * nrl); h[n][i] = (ga * ua) * fast_rcp(__builtin_fmaf(e, msq, msq)); }
;                 store8(H + (size_t)row * FF + col, h[0], h[1]);
;             }
	v_pk_fma_f32 v[38:39], v[38:39], v[190:191], v[190:191] op_sel_hi:[1,0,0]
	v_pk_fma_f32 v[40:41], v[40:41], v[190:191], v[190:191] op_sel_hi:[1,0,0]
	v_rcp_f32_e32 v46, v46
	v_rcp_f32_e32 v47, v47
	v_rcp_f32_e32 v48, v48
	v_rcp_f32_e32 v49, v49
	v_rcp_f32_e32 v38, v38
	v_rcp_f32_e32 v39, v39
	v_rcp_f32_e32 v40, v40
	v_rcp_f32_e32 v41, v41
	v_fmamk_f32 v190, v149, 0x3a800000, v161
	v_rsq_f32_e32 v193, v190
	v_pk_mul_f32 v[42:43], v[46:47], v[42:43]
	v_pk_mul_f32 v[44:45], v[48:49], v[44:45]
	v_pk_mul_f32 v[34:35], v[38:39], v[34:35]
	v_pk_mul_f32 v[36:37], v[40:41], v[36:37]
	v_cvt_pk_bf16_f32 v46, v42, v43
	v_cvt_pk_bf16_f32 v47, v44, v45
	v_cvt_pk_bf16_f32 v48, v34, v35
	v_cvt_pk_bf16_f32 v49, v36, v37
	v_mul_f32_e32 v192, 0xbfb8aa3b, v193
	v_pk_mul_f32 v[26:27], v[30:31], v[26:27]
	v_pk_mul_f32 v[28:29], v[32:33], v[28:29]
	v_pk_mul_f32 v[18:19], v[22:23], v[18:19]
	v_pk_mul_f32 v[20:21], v[24:25], v[20:21]
	v_pk_mul_f32 v[30:31], v[30:31], v[188:189] op_sel_hi:[1,0]
	v_pk_mul_f32 v[32:33], v[32:33], v[188:189] op_sel_hi:[1,0]
	v_pk_mul_f32 v[22:23], v[22:23], v[188:189] op_sel_hi:[1,0]
	v_pk_mul_f32 v[24:25], v[24:25], v[188:189] op_sel_hi:[1,0]
	v_exp_f32_e32 v30, v30
	v_exp_f32_e32 v31, v31
	v_exp_f32_e32 v32, v32
	v_exp_f32_e32 v33, v33
	v_exp_f32_e32 v22, v22
	v_exp_f32_e32 v23, v23
	v_exp_f32_e32 v24, v24
	v_exp_f32_e32 v25, v25
	global_store_dwordx4 v199, v[46:49], s[10:11]
	v_pk_fma_f32 v[30:31], v[30:31], v[186:187], v[186:187] op_sel_hi:[1,0,0]
	v_pk_fma_f32 v[32:33], v[32:33], v[186:187], v[186:187] op_sel_hi:[1,0,0]
	v_pk_fma_f32 v[22:23], v[22:23], v[186:187], v[186:187] op_sel_hi:[1,0,0]
	v_pk_fma_f32 v[24:25], v[24:25], v[186:187], v[186:187] op_sel_hi:[1,0,0]
	v_rcp_f32_e32 v30, v30
	v_rcp_f32_e32 v31, v31
	v_rcp_f32_e32 v32, v32
	v_rcp_f32_e32 v33, v33
	v_rcp_f32_e32 v22, v22
	v_rcp_f32_e32 v23, v23
	v_rcp_f32_e32 v24, v24
	v_rcp_f32_e32 v25, v25
	v_pk_mul_f32 v[26:27], v[30:31], v[26:27]
	v_pk_mul_f32 v[28:29], v[32:33], v[28:29]
	v_pk_mul_f32 v[18:19], v[22:23], v[18:19]
	v_pk_mul_f32 v[20:21], v[24:25], v[20:21]
	v_cvt_pk_bf16_f32 v30, v26, v27
	v_cvt_pk_bf16_f32 v31, v28, v29
	v_cvt_pk_bf16_f32 v32, v18, v19
	v_cvt_pk_bf16_f32 v33, v20, v21
	v_pk_mul_f32 v[10:11], v[14:15], v[10:11]
	v_pk_mul_f32 v[12:13], v[16:17], v[12:13]
	v_pk_mul_f32 v[2:3], v[6:7], v[2:3]
	v_pk_mul_f32 v[4:5], v[8:9], v[4:5]
	v_pk_mul_f32 v[14:15], v[14:15], v[192:193] op_sel_hi:[1,0]
	v_pk_mul_f32 v[16:17], v[16:17], v[192:193] op_sel_hi:[1,0]
	v_pk_mul_f32 v[6:7], v[6:7], v[192:193] op_sel_hi:[1,0]
	v_pk_mul_f32 v[8:9], v[8:9], v[192:193] op_sel_hi:[1,0]
	v_exp_f32_e32 v14, v14
	v_exp_f32_e32 v15, v15
	v_exp_f32_e32 v16, v16
	v_exp_f32_e32 v17, v17
	v_exp_f32_e32 v6, v6
	v_exp_f32_e32 v7, v7
	v_exp_f32_e32 v8, v8
	v_exp_f32_e32 v9, v9
	global_store_dwordx4 v200, v[30:33], s[10:11]
	v_pk_fma_f32 v[14:15], v[14:15], v[190:191], v[190:191] op_sel_hi:[1,0,0]
	v_pk_fma_f32 v[16:17], v[16:17], v[190:191], v[190:191] op_sel_hi:[1,0,0]
	v_pk_fma_f32 v[6:7], v[6:7], v[190:191], v[190:191] op_sel_hi:[1,0,0]
	v_pk_fma_f32 v[8:9], v[8:9], v[190:191], v[190:191] op_sel_hi:[1,0,0]
	v_rcp_f32_e32 v14, v14
	v_rcp_f32_e32 v15, v15
	v_rcp_f32_e32 v16, v16
	v_rcp_f32_e32 v17, v17
	v_rcp_f32_e32 v6, v6
	v_rcp_f32_e32 v7, v7
	v_rcp_f32_e32 v8, v8
	v_rcp_f32_e32 v9, v9
	v_pk_mul_f32 v[10:11], v[14:15], v[10:11]
	v_pk_mul_f32 v[12:13], v[16:17], v[12:13]
	v_pk_mul_f32 v[2:3], v[6:7], v[2:3]
	v_pk_mul_f32 v[4:5], v[8:9], v[4:5]
	v_cvt_pk_bf16_f32 v14, v10, v11
	v_cvt_pk_bf16_f32 v15, v12, v13
	v_cvt_pk_bf16_f32 v16, v2, v3
	v_cvt_pk_bf16_f32 v17, v4, v5
	s_andn2_b64 vcc, exec, s[4:5]
	s_mov_b64 s[4:5], -1
	global_store_dwordx4 v201, v[14:17], s[10:11]
	s_cbranch_vccnz .LBB0_175
	s_andn2_b64 vcc, exec, s[8:9]
	s_cbranch_vccnz .LBB0_174
	s_barrier
	s_branch .LBB0_174

; DI float fast_exp2(float x) { return __builtin_amdgcn_exp2f(x); }
; DI float fast_rcp(float x) { return __builtin_amdgcn_rcpf(x); }
;     DI void operator()(Acc& acc, const pg8::Unit& u, int wr, int wc, int fr, int fq, const Pre& pr) const {
;     ...
;                 const int row = u.pm * 256 + ai * 128 + wr * 64 + m * 16 + fr;
;                 const float msq = msq_of(pr.v[ai * 4 + m]), nrl = -1.4426950408889634f * __builtin_amdgcn_rsqf(msq);
;                 f32x4 h[2];
; #pragma unroll
;                 for (int n = 0; n < 2; ++n)
; #pragma unroll
;                     for (int i = 0; i < 4; ++i) { const float ga = acc[ai][0][m][n][i], ua = acc[ai][1][m][n][i];
;                         const float e = fast_exp2(ga * nrl); h[n][i] = (ga * ua) * fast_rcp(__builtin_fmaf(e, msq, msq)); }
;                 store8(H + (size_t)row * FF + col, h[0], h[1]);
.LBB0_1237:
	v_fmamk_f32 v186, v164, 0x3a800000, v159
	v_rsq_f32_e32 v189, v186
	v_lshl_or_b32 v202, s60, 7, v157
	v_lshlrev_b32_e32 v202, 1, v202
	v_mad_u32_u24 v194, v154, s59, v202
	v_mul_f32_e32 v188, 0xbfb8aa3b, v189
	v_fmamk_f32 v190, v163, 0x3a800000, v159
	v_rsq_f32_e32 v193, v190
	v_add_u32_e32 v195, 0x16000, v194
	v_add_u32_e32 v196, 0x2c000, v194
	v_add_u32_e32 v197, 0x42000, v194
	v_add_u32_e32 v198, 0xb0000, v194
	v_add_u32_e32 v199, 0xc6000, v194
	v_add_u32_e32 v200, 0xdc000, v194
	v_add_u32_e32 v201, 0xf2000, v194
	v_mul_f32_e32 v192, 0xbfb8aa3b, v193
	v_pk_mul_f32 v[122:123], v[126:127], v[122:123]
	v_pk_mul_f32 v[124:125], v[128:129], v[124:125]
	v_pk_mul_f32 v[114:115], v[118:119], v[114:115]
	v_pk_mul_f32 v[116:117], v[120:121], v[116:117]
	v_pk_mul_f32 v[126:127], v[126:127], v[188:189] op_sel_hi:[1,0]
	v_pk_mul_f32 v[128:129], v[128:129], v[188:189] op_sel_hi:[1,0]
	v_pk_mul_f32 v[118:119], v[118:119], v[188:189] op_sel_hi:[1,0]
	v_pk_mul_f32 v[120:121], v[120:121], v[188:189] op_sel_hi:[1,0]
	v_exp_f32_e32 v126, v126
	v_exp_f32_e32 v127, v127
	v_exp_f32_e32 v128, v128
	v_exp_f32_e32 v129, v129
	v_exp_f32_e32 v118, v118
	v_exp_f32_e32 v119, v119
	v_exp_f32_e32 v120, v120
	v_exp_f32_e32 v121, v121
	v_pk_fma_f32 v[126:127], v[126:127], v[186:187], v[186:187] op_sel_hi:[1,0,0]
	v_pk_fma_f32 v[128:129], v[128:129], v[186:187], v[186:187] op_sel_hi:[1,0,0]
	v_pk_fma_f32 v[118:119], v[118:119], v[186:187], v[186:187] op_sel_hi:[1,0,0]
	v_pk_fma_f32 v[120:121], v[120:121], v[186:187], v[186:187] op_sel_hi:[1,0,0]
	v_rcp_f32_e32 v126, v126
	v_rcp_f32_e32 v127, v127
	v_rcp_f32_e32 v128, v128
	v_rcp_f32_e32 v129, v129
	v_rcp_f32_e32 v118, v118
	v_rcp_f32_e32 v119, v119
	v_rcp_f32_e32 v120, v120
	v_rcp_f32_e32 v121, v121
	v_fmamk_f32 v186, v162, 0x3a800000, v159
	v_rsq_f32_e32 v189, v186
	v_pk_mul_f32 v[122:123], v[126:127], v[122:123]
	v_pk_mul_f32 v[124:125], v[128:129], v[124:125]
	v_pk_mul_f32 v[114:115], v[118:119], v[114:115]
	v_pk_mul_f32 v[116:117], v[120:121], v[116:117]
	v_cvt_pk_bf16_f32 v126, v122, v123
	v_cvt_pk_bf16_f32 v127, v124, v125
	v_cvt_pk_bf16_f32 v128, v114, v115
	v_cvt_pk_bf16_f32 v129, v116, v117
	v_mul_f32_e32 v188, 0xbfb8aa3b, v189
	v_pk_mul_f32 v[106:107], v[110:111], v[106:107]
	v_pk_mul_f32 v[108:109], v[112:113], v[108:109]
	v_pk_mul_f32 v[98:99], v[102:103], v[98:99]
	v_pk_mul_f32 v[100:101], v[104:105], v[100:101]
	v_pk_mul_f32 v[110:111], v[110:111], v[192:193] op_sel_hi:[1,0]
	v_pk_mul_f32 v[112:113], v[112:113], v[192:193] op_sel_hi:[1,0]
	v_pk_mul_f32 v[102:103], v[102:103], v[192:193] op_sel_hi:[1,0]
	v_pk_mul_f32 v[104:105], v[104:105], v[192:193] op_sel_hi:[1,0]
	v_exp_f32_e32 v110, v110
	v_exp_f32_e32 v111, v111
	v_exp_f32_e32 v112, v112
	v_exp_f32_e32 v113, v113
	v_exp_f32_e32 v102, v102
	v_exp_f32_e32 v103, v103
	v_exp_f32_e32 v104, v104
	v_exp_f32_e32 v105, v105
	global_store_dwordx4 v194, v[126:129], s[12:13]
	v_pk_fma_f32 v[110:111], v[110:111], v[190:191], v[190:191] op_sel_hi:[1,0,0]
	v_pk_fma_f32 v[112:113], v[112:113], v[190:191], v[190:191] op_sel_hi:[1,0,0]
	v_pk_fma_f32 v[102:103], v[102:103], v[190:191], v[190:191] op_sel_hi:[1,0,0]
	v_pk_fma_f32 v[104:105], v[104:105], v[190:191], v[190:191] op_sel_hi:[1,0,0]
	v_rcp_f32_e32 v110, v110
	v_rcp_f32_e32 v111, v111
	v_rcp_f32_e32 v112, v112
	v_rcp_f32_e32 v113, v113
	v_rcp_f32_e32 v102, v102
	v_rcp_f32_e32 v103, v103
	v_rcp_f32_e32 v104, v104
	v_rcp_f32_e32 v105, v105
	v_fmamk_f32 v190, v155, 0x3a800000, v159
	v_rsq_f32_e32 v193, v190
	v_pk_mul_f32 v[106:107], v[110:111], v[106:107]
	v_pk_mul_f32 v[108:109], v[112:113], v[108:109]
	v_pk_mul_f32 v[98:99], v[102:103], v[98:99]
	v_pk_mul_f32 v[100:101], v[104:105], v[100:101]
	v_cvt_pk_bf16_f32 v110, v106, v107
	v_cvt_pk_bf16_f32 v111, v108, v109
	v_cvt_pk_bf16_f32 v112, v98, v99
	v_cvt_pk_bf16_f32 v113, v100, v101
	v_mul_f32_e32 v192, 0xbfb8aa3b, v193
	v_pk_mul_f32 v[90:91], v[94:95], v[90:91]
	v_pk_mul_f32 v[92:93], v[96:97], v[92:93]
	v_pk_mul_f32 v[82:83], v[86:87], v[82:83]
	v_pk_mul_f32 v[84:85], v[88:89], v[84:85]
	v_pk_mul_f32 v[94:95], v[94:95], v[188:189] op_sel_hi:[1,0]
	v_pk_mul_f32 v[96:97], v[96:97], v[188:189] op_sel_hi:[1,0]
	v_pk_mul_f32 v[86:87], v[86:87], v[188:189] op_sel_hi:[1,0]
	v_pk_mul_f32 v[88:89], v[88:89], v[188:189] op_sel_hi:[1,0]
	v_exp_f32_e32 v94, v94
	v_exp_f32_e32 v95, v95
	v_exp_f32_e32 v96, v96
	v_exp_f32_e32 v97, v97
	v_exp_f32_e32 v86, v86
	v_exp_f32_e32 v87, v87
	v_exp_f32_e32 v88, v88
	v_exp_f32_e32 v89, v89
	global_store_dwordx4 v195, v[110:113], s[12:13]
	v_pk_fma_f32 v[94:95], v[94:95], v[186:187], v[186:187] op_sel_hi:[1,0,0]
	v_pk_fma_f32 v[96:97], v[96:97], v[186:187], v[186:187] op_sel_hi:[1,0,0]
	v_pk_fma_f32 v[86:87], v[86:87], v[186:187], v[186:187] op_sel_hi:[1,0,0]
	v_pk_fma_f32 v[88:89], v[88:89], v[186:187], v[186:187] op_sel_hi:[1,0,0]
	v_rcp_f32_e32 v94, v94
	v_rcp_f32_e32 v95, v95
	v_rcp_f32_e32 v96, v96
	v_rcp_f32_e32 v97, v97
	v_rcp_f32_e32 v86, v86
	v_rcp_f32_e32 v87, v87
	v_rcp_f32_e32 v88, v88
	v_rcp_f32_e32 v89, v89
	v_fmamk_f32 v186, v153, 0x3a800000, v159
	v_rsq_f32_e32 v189, v186
	v_pk_mul_f32 v[90:91], v[94:95], v[90:91]
	v_pk_mul_f32 v[92:93], v[96:97], v[92:93]
	v_pk_mul_f32 v[82:83], v[86:87], v[82:83]
	v_pk_mul_f32 v[84:85], v[88:89], v[84:85]
	v_cvt_pk_bf16_f32 v94, v90, v91
	v_cvt_pk_bf16_f32 v95, v92, v93
	v_cvt_pk_bf16_f32 v96, v82, v83
	v_cvt_pk_bf16_f32 v97, v84, v85
	v_mul_f32_e32 v188, 0xbfb8aa3b, v189
	v_pk_mul_f32 v[74:75], v[78:79], v[74:75]
	v_pk_mul_f32 v[76:77], v[80:81], v[76:77]
	v_pk_mul_f32 v[66:67], v[70:71], v[66:67]
	v_pk_mul_f32 v[68:69], v[72:73], v[68:69]
; DI float fast_exp2(float x) { return __builtin_amdgcn_exp2f(x); }
; DI float fast_rcp(float x) { return __builtin_amdgcn_rcpf(x); }
;     DI void operator()(Acc& acc, const pg8::Unit& u, int wr, int wc, int fr, int fq, const Pre& pr) const {
;     ...
;                 const float msq = msq_of(pr.v[ai * 4 + m]), nrl = -1.4426950408889634f * __builtin_amdgcn_rsqf(msq);
;                 f32x4 h[2];
; #pragma unroll
;                 for (int n = 0; n < 2; ++n)
; #pragma unroll
;                     for (int i = 0; i < 4; ++i) { const float ga = acc[ai][0][m][n][i], ua = acc[ai][1][m][n][i];
;                         const float e = fast_exp2(ga * nrl); h[n][i] = (ga * ua) * fast_rcp(__builtin_fmaf(e, msq, msq)); }
;                 store8(H + (size_t)row * FF + col, h[0], h[1]);
	v_pk_mul_f32 v[78:79], v[78:79], v[192:193] op_sel_hi:[1,0]
	v_pk_mul_f32 v[80:81], v[80:81], v[192:193] op_sel_hi:[1,0]
	v_pk_mul_f32 v[70:71], v[70:71], v[192:193] op_sel_hi:[1,0]
	v_pk_mul_f32 v[72:73], v[72:73], v[192:193] op_sel_hi:[1,0]
	v_exp_f32_e32 v78, v78
	v_exp_f32_e32 v79, v79
	v_exp_f32_e32 v80, v80
	v_exp_f32_e32 v81, v81
	v_exp_f32_e32 v70, v70
	v_exp_f32_e32 v71, v71
	v_exp_f32_e32 v72, v72
	v_exp_f32_e32 v73, v73
	global_store_dwordx4 v196, v[94:97], s[12:13]
	v_pk_fma_f32 v[78:79], v[78:79], v[190:191], v[190:191] op_sel_hi:[1,0,0]
	v_pk_fma_f32 v[80:81], v[80:81], v[190:191], v[190:191] op_sel_hi:[1,0,0]
	v_pk_fma_f32 v[70:71], v[70:71], v[190:191], v[190:191] op_sel_hi:[1,0,0]
	v_pk_fma_f32 v[72:73], v[72:73], v[190:191], v[190:191] op_sel_hi:[1,0,0]
	v_rcp_f32_e32 v78, v78
	v_rcp_f32_e32 v79, v79
	v_rcp_f32_e32 v80, v80
	v_rcp_f32_e32 v81, v81
	v_rcp_f32_e32 v70, v70
	v_rcp_f32_e32 v71, v71
	v_rcp_f32_e32 v72, v72
	v_rcp_f32_e32 v73, v73
	v_fmamk_f32 v190, v151, 0x3a800000, v159
	v_rsq_f32_e32 v193, v190
	v_pk_mul_f32 v[74:75], v[78:79], v[74:75]
	v_pk_mul_f32 v[76:77], v[80:81], v[76:77]
	v_pk_mul_f32 v[66:67], v[70:71], v[66:67]
	v_pk_mul_f32 v[68:69], v[72:73], v[68:69]
	v_cvt_pk_bf16_f32 v78, v74, v75
	v_cvt_pk_bf16_f32 v79, v76, v77
	v_cvt_pk_bf16_f32 v80, v66, v67
	v_cvt_pk_bf16_f32 v81, v68, v69
	v_mul_f32_e32 v192, 0xbfb8aa3b, v193
	v_pk_mul_f32 v[58:59], v[62:63], v[58:59]
	v_pk_mul_f32 v[60:61], v[64:65], v[60:61]
	v_pk_mul_f32 v[50:51], v[54:55], v[50:51]
	v_pk_mul_f32 v[52:53], v[56:57], v[52:53]
	v_pk_mul_f32 v[62:63], v[62:63], v[188:189] op_sel_hi:[1,0]
	v_pk_mul_f32 v[64:65], v[64:65], v[188:189] op_sel_hi:[1,0]
	v_pk_mul_f32 v[54:55], v[54:55], v[188:189] op_sel_hi:[1,0]
	v_pk_mul_f32 v[56:57], v[56:57], v[188:189] op_sel_hi:[1,0]
	v_exp_f32_e32 v62, v62
	v_exp_f32_e32 v63, v63
	v_exp_f32_e32 v64, v64
	v_exp_f32_e32 v65, v65
	v_exp_f32_e32 v54, v54
	v_exp_f32_e32 v55, v55
	v_exp_f32_e32 v56, v56
	v_exp_f32_e32 v57, v57
	global_store_dwordx4 v197, v[78:81], s[12:13]
	v_pk_fma_f32 v[62:63], v[62:63], v[186:187], v[186:187] op_sel_hi:[1,0,0]
	v_pk_fma_f32 v[64:65], v[64:65], v[186:187], v[186:187] op_sel_hi:[1,0,0]
	v_pk_fma_f32 v[54:55], v[54:55], v[186:187], v[186:187] op_sel_hi:[1,0,0]
	v_pk_fma_f32 v[56:57], v[56:57], v[186:187], v[186:187] op_sel_hi:[1,0,0]
	v_rcp_f32_e32 v62, v62
	v_rcp_f32_e32 v63, v63
	v_rcp_f32_e32 v64, v64
	v_rcp_f32_e32 v65, v65
	v_rcp_f32_e32 v54, v54
	v_rcp_f32_e32 v55, v55
	v_rcp_f32_e32 v56, v56
	v_rcp_f32_e32 v57, v57
	v_fmamk_f32 v186, v149, 0x3a800000, v159
	v_rsq_f32_e32 v189, v186
	v_pk_mul_f32 v[58:59], v[62:63], v[58:59]
	v_pk_mul_f32 v[60:61], v[64:65], v[60:61]
	v_pk_mul_f32 v[50:51], v[54:55], v[50:51]
	v_pk_mul_f32 v[52:53], v[56:57], v[52:53]
	v_cvt_pk_bf16_f32 v62, v58, v59
	v_cvt_pk_bf16_f32 v63, v60, v61
	v_cvt_pk_bf16_f32 v64, v50, v51
	v_cvt_pk_bf16_f32 v65, v52, v53
	v_mul_f32_e32 v188, 0xbfb8aa3b, v189
	v_pk_mul_f32 v[42:43], v[46:47], v[42:43]
	v_pk_mul_f32 v[44:45], v[48:49], v[44:45]
	v_pk_mul_f32 v[34:35], v[38:39], v[34:35]
	v_pk_mul_f32 v[36:37], v[40:41], v[36:37]
	v_pk_mul_f32 v[46:47], v[46:47], v[192:193] op_sel_hi:[1,0]
	v_pk_mul_f32 v[48:49], v[48:49], v[192:193] op_sel_hi:[1,0]
	v_pk_mul_f32 v[38:39], v[38:39], v[192:193] op_sel_hi:[1,0]
	v_pk_mul_f32 v[40:41], v[40:41], v[192:193] op_sel_hi:[1,0]
	v_exp_f32_e32 v46, v46
	v_exp_f32_e32 v47, v47
	v_exp_f32_e32 v48, v48
	v_exp_f32_e32 v49, v49
	v_exp_f32_e32 v38, v38
	v_exp_f32_e32 v39, v39
	v_exp_f32_e32 v40, v40
	v_exp_f32_e32 v41, v41
	global_store_dwordx4 v198, v[62:65], s[12:13]
	v_pk_fma_f32 v[46:47], v[46:47], v[190:191], v[190:191] op_sel_hi:[1,0,0]
	v_pk_fma_f32 v[48:49], v[48:49], v[190:191], v[190:191] op_sel_hi:[1,0,0]
; DI float fast_exp2(float x) { return __builtin_amdgcn_exp2f(x); }
; DI float fast_rcp(float x) { return __builtin_amdgcn_rcpf(x); }
; #define PG8_BAR __builtin_amdgcn_s_barrier()
; template <class Epi, class Sched>
; DI void gemm_phase(LAS unsigned char* lds, const Gemm g, const Sched& S, const Epi& E) {
;     ...
;         if (!has_next) break;
;         if (!(Epi::CHAIN && cur.src == 0)) {
; #pragma unroll
;             for (int a = 0; a < 2; ++a)
; #pragma unroll
;                 for (int b = 0; b < 2; ++b)
; #pragma unroll
;                     for (int m = 0; m < 4; ++m)
; #pragma unroll
;                         for (int n = 0; n < 2; ++n) acc[a][b][m][n] = (f32x4){0.f, 0.f, 0.f, 0.f};
;         }
;         cur = nxt; cA = nA; cB = nB; ++ui;
;         if (wr == 1) PG8_BAR;
;     DI void operator()(Acc& acc, const pg8::Unit& u, int wr, int wc, int fr, int fq, const Pre& pr) const {
;     ...
;                 const float msq = msq_of(pr.v[ai * 4 + m]), nrl = -1.4426950408889634f * __builtin_amdgcn_rsqf(msq);
;                 f32x4 h[2];
; #pragma unroll
;                 for (int n = 0; n < 2; ++n)
; #pragma unroll
;                     for (int i = 0; i < 4; ++i) { const float ga = acc[ai][0][m][n][i], ua = acc[ai][1][m][n][i];
;                         const float e = fast_exp2(ga * nrl); h[n][i] = (ga * ua) * fast_rcp(__builtin_fmaf(e, msq, msq)); }
;                 store8(H + (size_t)row * FF + col, h[0], h[1]);
	v_pk_fma_f32 v[38:39], v[38:39], v[190:191], v[190:191] op_sel_hi:[1,0,0]
	v_pk_fma_f32 v[40:41], v[40:41], v[190:191], v[190:191] op_sel_hi:[1,0,0]
	v_rcp_f32_e32 v46, v46
	v_rcp_f32_e32 v47, v47
	v_rcp_f32_e32 v48, v48
	v_rcp_f32_e32 v49, v49
	v_rcp_f32_e32 v38, v38
	v_rcp_f32_e32 v39, v39
	v_rcp_f32_e32 v40, v40
	v_rcp_f32_e32 v41, v41
	v_fmamk_f32 v190, v147, 0x3a800000, v159
	v_rsq_f32_e32 v193, v190
	v_pk_mul_f32 v[42:43], v[46:47], v[42:43]
	v_pk_mul_f32 v[44:45], v[48:49], v[44:45]
	v_pk_mul_f32 v[34:35], v[38:39], v[34:35]
	v_pk_mul_f32 v[36:37], v[40:41], v[36:37]
	v_cvt_pk_bf16_f32 v46, v42, v43
	v_cvt_pk_bf16_f32 v47, v44, v45
	v_cvt_pk_bf16_f32 v48, v34, v35
	v_cvt_pk_bf16_f32 v49, v36, v37
	v_mul_f32_e32 v192, 0xbfb8aa3b, v193
	v_pk_mul_f32 v[26:27], v[30:31], v[26:27]
	v_pk_mul_f32 v[28:29], v[32:33], v[28:29]
	v_pk_mul_f32 v[18:19], v[22:23], v[18:19]
	v_pk_mul_f32 v[20:21], v[24:25], v[20:21]
	v_pk_mul_f32 v[30:31], v[30:31], v[188:189] op_sel_hi:[1,0]
	v_pk_mul_f32 v[32:33], v[32:33], v[188:189] op_sel_hi:[1,0]
	v_pk_mul_f32 v[22:23], v[22:23], v[188:189] op_sel_hi:[1,0]
	v_pk_mul_f32 v[24:25], v[24:25], v[188:189] op_sel_hi:[1,0]
	v_exp_f32_e32 v30, v30
	v_exp_f32_e32 v31, v31
	v_exp_f32_e32 v32, v32
	v_exp_f32_e32 v33, v33
	v_exp_f32_e32 v22, v22
	v_exp_f32_e32 v23, v23
	v_exp_f32_e32 v24, v24
	v_exp_f32_e32 v25, v25
	global_store_dwordx4 v199, v[46:49], s[12:13]
	v_pk_fma_f32 v[30:31], v[30:31], v[186:187], v[186:187] op_sel_hi:[1,0,0]
	v_pk_fma_f32 v[32:33], v[32:33], v[186:187], v[186:187] op_sel_hi:[1,0,0]
	v_pk_fma_f32 v[22:23], v[22:23], v[186:187], v[186:187] op_sel_hi:[1,0,0]
	v_pk_fma_f32 v[24:25], v[24:25], v[186:187], v[186:187] op_sel_hi:[1,0,0]
	v_rcp_f32_e32 v30, v30
	v_rcp_f32_e32 v31, v31
	v_rcp_f32_e32 v32, v32
	v_rcp_f32_e32 v33, v33
	v_rcp_f32_e32 v22, v22
	v_rcp_f32_e32 v23, v23
	v_rcp_f32_e32 v24, v24
	v_rcp_f32_e32 v25, v25
	v_pk_mul_f32 v[26:27], v[30:31], v[26:27]
	v_pk_mul_f32 v[28:29], v[32:33], v[28:29]
	v_pk_mul_f32 v[18:19], v[22:23], v[18:19]
	v_pk_mul_f32 v[20:21], v[24:25], v[20:21]
	v_cvt_pk_bf16_f32 v30, v26, v27
	v_cvt_pk_bf16_f32 v31, v28, v29
	v_cvt_pk_bf16_f32 v32, v18, v19
	v_cvt_pk_bf16_f32 v33, v20, v21
	v_pk_mul_f32 v[10:11], v[14:15], v[10:11]
	v_pk_mul_f32 v[12:13], v[16:17], v[12:13]
	v_pk_mul_f32 v[2:3], v[6:7], v[2:3]
	v_pk_mul_f32 v[4:5], v[8:9], v[4:5]
	v_pk_mul_f32 v[14:15], v[14:15], v[192:193] op_sel_hi:[1,0]
	v_pk_mul_f32 v[16:17], v[16:17], v[192:193] op_sel_hi:[1,0]
	v_pk_mul_f32 v[6:7], v[6:7], v[192:193] op_sel_hi:[1,0]
	v_pk_mul_f32 v[8:9], v[8:9], v[192:193] op_sel_hi:[1,0]
	v_exp_f32_e32 v14, v14
	v_exp_f32_e32 v15, v15
	v_exp_f32_e32 v16, v16
	v_exp_f32_e32 v17, v17
	v_exp_f32_e32 v6, v6
	v_exp_f32_e32 v7, v7
	v_exp_f32_e32 v8, v8
	v_exp_f32_e32 v9, v9
	global_store_dwordx4 v200, v[30:33], s[12:13]
	v_pk_fma_f32 v[14:15], v[14:15], v[190:191], v[190:191] op_sel_hi:[1,0,0]
	v_pk_fma_f32 v[16:17], v[16:17], v[190:191], v[190:191] op_sel_hi:[1,0,0]
	v_pk_fma_f32 v[6:7], v[6:7], v[190:191], v[190:191] op_sel_hi:[1,0,0]
	v_pk_fma_f32 v[8:9], v[8:9], v[190:191], v[190:191] op_sel_hi:[1,0,0]
	v_rcp_f32_e32 v14, v14
	v_rcp_f32_e32 v15, v15
	v_rcp_f32_e32 v16, v16
	v_rcp_f32_e32 v17, v17
	v_rcp_f32_e32 v6, v6
	v_rcp_f32_e32 v7, v7
	v_rcp_f32_e32 v8, v8
	v_rcp_f32_e32 v9, v9
	v_pk_mul_f32 v[10:11], v[14:15], v[10:11]
	v_pk_mul_f32 v[12:13], v[16:17], v[12:13]
	v_pk_mul_f32 v[2:3], v[6:7], v[2:3]
	v_pk_mul_f32 v[4:5], v[8:9], v[4:5]
	v_cvt_pk_bf16_f32 v14, v10, v11
	v_cvt_pk_bf16_f32 v15, v12, v13
	v_cvt_pk_bf16_f32 v16, v2, v3
	v_cvt_pk_bf16_f32 v17, v4, v5
	s_andn2_b64 vcc, exec, s[4:5]
	s_mov_b64 s[4:5], -1
	global_store_dwordx4 v201, v[14:17], s[12:13]
	s_cbranch_vccnz .LBB0_1230
	s_andn2_b64 vcc, exec, s[10:11]
	s_cbranch_vccnz .LBB0_1229
	s_barrier
	s_branch .LBB0_1229
